# K-split sample tiles: accumulator blocks transposed through a wave-private LDS slot so each f32 atomic instruction covers 4 rows x 64 contiguous bytes (4 full requests instead of 16 sparse ones); glob
# speedup vs baseline: 1.0253x; 1.0182x over previous
.LBB0_50:
	s_andn2_b64 vcc, exec, s[18:19]
	s_cbranch_vccnz .LBB0_52
	v_and_b32_e32 v182, 15, v219
	v_lshrrev_b32_e32 v183, 4, v219
	v_lshrrev_b32_e32 v180, 6, v211
	v_lshlrev_b32_e32 v180, 11, v180
	v_lshl_add_u32 v181, v183, 6, v180
	v_lshl_add_u32 v181, v182, 2, v181
	v_lshl_add_u32 v180, v182, 6, v180
	v_lshl_add_u32 v180, v183, 4, v180
	v_sub_u32_e32 v184, v183, v182
	v_lshlrev_b32_e32 v184, 12, v184
	v_lshlrev_b32_e32 v185, 2, v183
	v_sub_u32_e32 v185, v182, v185
	v_lshlrev_b32_e32 v185, 2, v185
	v_add_u32_e32 v184, v184, v185
	v_mov_b32_e32 v160, v184
	v_ashrrev_i32_e32 v161, 31, v160
	v_add_u32_e32 v162, 0x4000, v184
	v_ashrrev_i32_e32 v163, 31, v162
	v_add_u32_e32 v164, 0x8000, v184
	v_ashrrev_i32_e32 v165, 31, v164
	v_add_u32_e32 v166, 0xc000, v184
	v_ashrrev_i32_e32 v167, 31, v166
	v_lshlrev_b64 v[142:143], 12, v[142:143]
	v_lshl_add_u64 v[142:143], s[8:9], 0, v[142:143]
	v_lshlrev_b64 v[146:147], 2, v[148:149]
	v_lshl_add_u64 v[142:143], v[142:143], 0, v[146:147]
	s_waitcnt vmcnt(0)
	ds_write_b128 v180, v[126:129] offset:0
	ds_write_b128 v180, v[122:125] offset:1024
	s_nop 1
	s_waitcnt lgkmcnt(0)
	ds_read_b32 v168, v181 offset:0
	ds_read_b32 v169, v181 offset:256
	ds_read_b32 v170, v181 offset:512
	ds_read_b32 v171, v181 offset:768
	ds_read_b32 v172, v181 offset:1024
	ds_read_b32 v173, v181 offset:1280
	ds_read_b32 v174, v181 offset:1536
	ds_read_b32 v175, v181 offset:1792
	s_waitcnt lgkmcnt(0)
	v_lshl_add_u64 v[176:177], v[142:143], 0, v[160:161]
	global_atomic_add_f32 v[176:177], v168, off offset:0
	v_lshl_add_u64 v[178:179], v[142:143], 0, v[162:163]
	global_atomic_add_f32 v[178:179], v169, off offset:0
	v_lshl_add_u64 v[176:177], v[142:143], 0, v[164:165]
	global_atomic_add_f32 v[176:177], v170, off offset:0
	v_lshl_add_u64 v[178:179], v[142:143], 0, v[166:167]
	global_atomic_add_f32 v[178:179], v171, off offset:0
	v_lshl_add_u64 v[176:177], v[142:143], 0, v[160:161]
	global_atomic_add_f32 v[176:177], v172, off offset:64
	v_lshl_add_u64 v[178:179], v[142:143], 0, v[162:163]
	global_atomic_add_f32 v[178:179], v173, off offset:64
	v_lshl_add_u64 v[176:177], v[142:143], 0, v[164:165]
	global_atomic_add_f32 v[176:177], v174, off offset:64
	v_lshl_add_u64 v[178:179], v[142:143], 0, v[166:167]
	global_atomic_add_f32 v[178:179], v175, off offset:64
	v_lshlrev_b64 v[122:123], 12, v[144:145]
	v_lshl_add_u64 v[122:123], s[8:9], 0, v[122:123]
	v_lshl_add_u64 v[122:123], v[122:123], 0, v[146:147]
	ds_write_b128 v180, v[118:121] offset:0
	ds_write_b128 v180, v[114:117] offset:1024
	s_nop 1
	s_waitcnt lgkmcnt(0)
	ds_read_b32 v168, v181 offset:0
	ds_read_b32 v169, v181 offset:256
	ds_read_b32 v170, v181 offset:512
	ds_read_b32 v171, v181 offset:768
	ds_read_b32 v172, v181 offset:1024
	ds_read_b32 v173, v181 offset:1280
	ds_read_b32 v174, v181 offset:1536
	ds_read_b32 v175, v181 offset:1792
	s_waitcnt lgkmcnt(0)
	v_lshl_add_u64 v[176:177], v[122:123], 0, v[160:161]
	global_atomic_add_f32 v[176:177], v168, off offset:0
	v_lshl_add_u64 v[178:179], v[122:123], 0, v[162:163]
	global_atomic_add_f32 v[178:179], v169, off offset:0
	v_lshl_add_u64 v[176:177], v[122:123], 0, v[164:165]
	global_atomic_add_f32 v[176:177], v170, off offset:0
	v_lshl_add_u64 v[178:179], v[122:123], 0, v[166:167]
	global_atomic_add_f32 v[178:179], v171, off offset:0
	v_lshl_add_u64 v[176:177], v[122:123], 0, v[160:161]
	global_atomic_add_f32 v[176:177], v172, off offset:64
	v_lshl_add_u64 v[178:179], v[122:123], 0, v[162:163]
	global_atomic_add_f32 v[178:179], v173, off offset:64
	v_lshl_add_u64 v[176:177], v[122:123], 0, v[164:165]
	global_atomic_add_f32 v[176:177], v174, off offset:64
	v_lshl_add_u64 v[178:179], v[122:123], 0, v[166:167]
	global_atomic_add_f32 v[178:179], v175, off offset:64
	v_lshlrev_b64 v[114:115], 12, v[140:141]
	v_lshl_add_u64 v[114:115], s[8:9], 0, v[114:115]
	v_lshl_add_u64 v[114:115], v[114:115], 0, v[146:147]
	ds_write_b128 v180, v[110:113] offset:0
	ds_write_b128 v180, v[106:109] offset:1024
	s_nop 1
	s_waitcnt lgkmcnt(0)
	ds_read_b32 v168, v181 offset:0
	ds_read_b32 v169, v181 offset:256
	ds_read_b32 v170, v181 offset:512
	ds_read_b32 v171, v181 offset:768
	ds_read_b32 v172, v181 offset:1024
	ds_read_b32 v173, v181 offset:1280
	ds_read_b32 v174, v181 offset:1536
	ds_read_b32 v175, v181 offset:1792
	s_waitcnt lgkmcnt(0)
	v_lshl_add_u64 v[176:177], v[114:115], 0, v[160:161]
	global_atomic_add_f32 v[176:177], v168, off offset:0
	v_lshl_add_u64 v[178:179], v[114:115], 0, v[162:163]
	global_atomic_add_f32 v[178:179], v169, off offset:0
	v_lshl_add_u64 v[176:177], v[114:115], 0, v[164:165]
	global_atomic_add_f32 v[176:177], v170, off offset:0
	v_lshl_add_u64 v[178:179], v[114:115], 0, v[166:167]
	global_atomic_add_f32 v[178:179], v171, off offset:0
	v_lshl_add_u64 v[176:177], v[114:115], 0, v[160:161]
	global_atomic_add_f32 v[176:177], v172, off offset:64
	v_lshl_add_u64 v[178:179], v[114:115], 0, v[162:163]
	global_atomic_add_f32 v[178:179], v173, off offset:64
	v_lshl_add_u64 v[176:177], v[114:115], 0, v[164:165]
	global_atomic_add_f32 v[176:177], v174, off offset:64
	v_lshl_add_u64 v[178:179], v[114:115], 0, v[166:167]
	global_atomic_add_f32 v[178:179], v175, off offset:64
	v_lshlrev_b64 v[106:107], 12, v[138:139]
	v_lshl_add_u64 v[106:107], s[8:9], 0, v[106:107]
	v_lshl_add_u64 v[106:107], v[106:107], 0, v[146:147]
	ds_write_b128 v180, v[86:89] offset:0
	ds_write_b128 v180, v[74:77] offset:1024
	s_nop 1
	s_waitcnt lgkmcnt(0)
	ds_read_b32 v168, v181 offset:0
	ds_read_b32 v169, v181 offset:256
	ds_read_b32 v170, v181 offset:512
	ds_read_b32 v171, v181 offset:768
	ds_read_b32 v172, v181 offset:1024
	ds_read_b32 v173, v181 offset:1280
	ds_read_b32 v174, v181 offset:1536
	ds_read_b32 v175, v181 offset:1792
	s_waitcnt lgkmcnt(0)
	v_lshl_add_u64 v[176:177], v[106:107], 0, v[160:161]
	global_atomic_add_f32 v[176:177], v168, off offset:0
	v_lshl_add_u64 v[178:179], v[106:107], 0, v[162:163]
	global_atomic_add_f32 v[178:179], v169, off offset:0
	v_lshl_add_u64 v[176:177], v[106:107], 0, v[164:165]
	global_atomic_add_f32 v[176:177], v170, off offset:0
	v_lshl_add_u64 v[178:179], v[106:107], 0, v[166:167]
	global_atomic_add_f32 v[178:179], v171, off offset:0
	v_lshl_add_u64 v[176:177], v[106:107], 0, v[160:161]
	global_atomic_add_f32 v[176:177], v172, off offset:64
	v_lshl_add_u64 v[178:179], v[106:107], 0, v[162:163]
	global_atomic_add_f32 v[178:179], v173, off offset:64
	v_lshl_add_u64 v[176:177], v[106:107], 0, v[164:165]
	global_atomic_add_f32 v[176:177], v174, off offset:64
	v_lshl_add_u64 v[178:179], v[106:107], 0, v[166:167]
	global_atomic_add_f32 v[178:179], v175, off offset:64
	ds_write_b128 v180, v[102:105] offset:0
	ds_write_b128 v180, v[98:101] offset:1024
	s_nop 1
	s_waitcnt lgkmcnt(0)
	ds_read_b32 v168, v181 offset:0
	ds_read_b32 v169, v181 offset:256
	ds_read_b32 v170, v181 offset:512
	ds_read_b32 v171, v181 offset:768
	ds_read_b32 v172, v181 offset:1024
	ds_read_b32 v173, v181 offset:1280
	ds_read_b32 v174, v181 offset:1536
	ds_read_b32 v175, v181 offset:1792
	s_waitcnt lgkmcnt(0)
	v_lshl_add_u64 v[176:177], v[142:143], 0, v[160:161]
	global_atomic_add_f32 v[176:177], v168, off offset:512
	v_lshl_add_u64 v[178:179], v[142:143], 0, v[162:163]
	global_atomic_add_f32 v[178:179], v169, off offset:512
	v_lshl_add_u64 v[176:177], v[142:143], 0, v[164:165]
	global_atomic_add_f32 v[176:177], v170, off offset:512
	v_lshl_add_u64 v[178:179], v[142:143], 0, v[166:167]
	global_atomic_add_f32 v[178:179], v171, off offset:512
	v_lshl_add_u64 v[176:177], v[142:143], 0, v[160:161]
	global_atomic_add_f32 v[176:177], v172, off offset:576
	v_lshl_add_u64 v[178:179], v[142:143], 0, v[162:163]
	global_atomic_add_f32 v[178:179], v173, off offset:576
	v_lshl_add_u64 v[176:177], v[142:143], 0, v[164:165]
	global_atomic_add_f32 v[176:177], v174, off offset:576
	v_lshl_add_u64 v[178:179], v[142:143], 0, v[166:167]
	global_atomic_add_f32 v[178:179], v175, off offset:576
	ds_write_b128 v180, v[94:97] offset:0
	ds_write_b128 v180, v[90:93] offset:1024
	s_nop 1
	s_waitcnt lgkmcnt(0)
	ds_read_b32 v168, v181 offset:0
	ds_read_b32 v169, v181 offset:256
	ds_read_b32 v170, v181 offset:512
	ds_read_b32 v171, v181 offset:768
	ds_read_b32 v172, v181 offset:1024
	ds_read_b32 v173, v181 offset:1280
	ds_read_b32 v174, v181 offset:1536
	ds_read_b32 v175, v181 offset:1792
	s_waitcnt lgkmcnt(0)
	v_lshl_add_u64 v[176:177], v[122:123], 0, v[160:161]
	global_atomic_add_f32 v[176:177], v168, off offset:512
	v_lshl_add_u64 v[178:179], v[122:123], 0, v[162:163]
	global_atomic_add_f32 v[178:179], v169, off offset:512
	v_lshl_add_u64 v[176:177], v[122:123], 0, v[164:165]
	global_atomic_add_f32 v[176:177], v170, off offset:512
	v_lshl_add_u64 v[178:179], v[122:123], 0, v[166:167]
	global_atomic_add_f32 v[178:179], v171, off offset:512
	v_lshl_add_u64 v[176:177], v[122:123], 0, v[160:161]
	global_atomic_add_f32 v[176:177], v172, off offset:576
	v_lshl_add_u64 v[178:179], v[122:123], 0, v[162:163]
	global_atomic_add_f32 v[178:179], v173, off offset:576
	v_lshl_add_u64 v[176:177], v[122:123], 0, v[164:165]
	global_atomic_add_f32 v[176:177], v174, off offset:576
	v_lshl_add_u64 v[178:179], v[122:123], 0, v[166:167]
	global_atomic_add_f32 v[178:179], v175, off offset:576
	ds_write_b128 v180, v[78:81] offset:0
	ds_write_b128 v180, v[66:69] offset:1024
	s_nop 1
	s_waitcnt lgkmcnt(0)
	ds_read_b32 v168, v181 offset:0
	ds_read_b32 v169, v181 offset:256
	ds_read_b32 v170, v181 offset:512
	ds_read_b32 v171, v181 offset:768
	ds_read_b32 v172, v181 offset:1024
	ds_read_b32 v173, v181 offset:1280
	ds_read_b32 v174, v181 offset:1536
	ds_read_b32 v175, v181 offset:1792
	s_waitcnt lgkmcnt(0)
	v_lshl_add_u64 v[176:177], v[114:115], 0, v[160:161]
	global_atomic_add_f32 v[176:177], v168, off offset:512
	v_lshl_add_u64 v[178:179], v[114:115], 0, v[162:163]
	global_atomic_add_f32 v[178:179], v169, off offset:512
	v_lshl_add_u64 v[176:177], v[114:115], 0, v[164:165]
	global_atomic_add_f32 v[176:177], v170, off offset:512
	v_lshl_add_u64 v[178:179], v[114:115], 0, v[166:167]
	global_atomic_add_f32 v[178:179], v171, off offset:512
	v_lshl_add_u64 v[176:177], v[114:115], 0, v[160:161]
	global_atomic_add_f32 v[176:177], v172, off offset:576
	v_lshl_add_u64 v[178:179], v[114:115], 0, v[162:163]
	global_atomic_add_f32 v[178:179], v173, off offset:576
	v_lshl_add_u64 v[176:177], v[114:115], 0, v[164:165]
	global_atomic_add_f32 v[176:177], v174, off offset:576
	v_lshl_add_u64 v[178:179], v[114:115], 0, v[166:167]
	global_atomic_add_f32 v[178:179], v175, off offset:576
	ds_write_b128 v180, v[62:65] offset:0
	ds_write_b128 v180, v[58:61] offset:1024
	s_nop 1
	s_waitcnt lgkmcnt(0)
	ds_read_b32 v168, v181 offset:0
	ds_read_b32 v169, v181 offset:256
	ds_read_b32 v170, v181 offset:512
	ds_read_b32 v171, v181 offset:768
	ds_read_b32 v172, v181 offset:1024
	ds_read_b32 v173, v181 offset:1280
	ds_read_b32 v174, v181 offset:1536
	ds_read_b32 v175, v181 offset:1792
	s_waitcnt lgkmcnt(0)
	v_lshl_add_u64 v[176:177], v[106:107], 0, v[160:161]
	global_atomic_add_f32 v[176:177], v168, off offset:512
	v_lshl_add_u64 v[178:179], v[106:107], 0, v[162:163]
	global_atomic_add_f32 v[178:179], v169, off offset:512
	v_lshl_add_u64 v[176:177], v[106:107], 0, v[164:165]
	global_atomic_add_f32 v[176:177], v170, off offset:512
	v_lshl_add_u64 v[178:179], v[106:107], 0, v[166:167]
	global_atomic_add_f32 v[178:179], v171, off offset:512
	v_lshl_add_u64 v[176:177], v[106:107], 0, v[160:161]
	global_atomic_add_f32 v[176:177], v172, off offset:576
	v_lshl_add_u64 v[178:179], v[106:107], 0, v[162:163]
	global_atomic_add_f32 v[178:179], v173, off offset:576
	v_lshl_add_u64 v[176:177], v[106:107], 0, v[164:165]
	global_atomic_add_f32 v[176:177], v174, off offset:576
	v_lshl_add_u64 v[178:179], v[106:107], 0, v[166:167]
	global_atomic_add_f32 v[178:179], v175, off offset:576
	v_lshlrev_b64 v[58:59], 12, v[136:137]
	v_lshl_add_u64 v[58:59], s[8:9], 0, v[58:59]
	v_lshlrev_b64 v[60:61], 12, v[134:135]
	v_lshl_add_u64 v[58:59], v[58:59], 0, v[146:147]
	v_lshl_add_u64 v[60:61], s[8:9], 0, v[60:61]
	ds_write_b128 v180, v[82:85] offset:0
	ds_write_b128 v180, v[70:73] offset:1024
	s_nop 1
	s_waitcnt lgkmcnt(0)
	ds_read_b32 v168, v181 offset:0
	ds_read_b32 v169, v181 offset:256
	ds_read_b32 v170, v181 offset:512
	ds_read_b32 v171, v181 offset:768
	ds_read_b32 v172, v181 offset:1024
	ds_read_b32 v173, v181 offset:1280
	ds_read_b32 v174, v181 offset:1536
	ds_read_b32 v175, v181 offset:1792
	s_waitcnt lgkmcnt(0)
	v_lshl_add_u64 v[176:177], v[58:59], 0, v[160:161]
	global_atomic_add_f32 v[176:177], v168, off offset:0
	v_lshl_add_u64 v[178:179], v[58:59], 0, v[162:163]
	global_atomic_add_f32 v[178:179], v169, off offset:0
	v_lshl_add_u64 v[176:177], v[58:59], 0, v[164:165]
	global_atomic_add_f32 v[176:177], v170, off offset:0
	v_lshl_add_u64 v[178:179], v[58:59], 0, v[166:167]
	global_atomic_add_f32 v[178:179], v171, off offset:0
	v_lshl_add_u64 v[176:177], v[58:59], 0, v[160:161]
	global_atomic_add_f32 v[176:177], v172, off offset:64
	v_lshl_add_u64 v[178:179], v[58:59], 0, v[162:163]
	global_atomic_add_f32 v[178:179], v173, off offset:64
	v_lshl_add_u64 v[176:177], v[58:59], 0, v[164:165]
	global_atomic_add_f32 v[176:177], v174, off offset:64
	v_lshl_add_u64 v[178:179], v[58:59], 0, v[166:167]
	global_atomic_add_f32 v[178:179], v175, off offset:64
	v_lshl_add_u64 v[60:61], v[60:61], 0, v[146:147]
	ds_write_b128 v180, v[54:57] offset:0
	ds_write_b128 v180, v[50:53] offset:1024
	s_nop 1
	s_waitcnt lgkmcnt(0)
	ds_read_b32 v168, v181 offset:0
	ds_read_b32 v169, v181 offset:256
	ds_read_b32 v170, v181 offset:512
	ds_read_b32 v171, v181 offset:768
	ds_read_b32 v172, v181 offset:1024
	ds_read_b32 v173, v181 offset:1280
	ds_read_b32 v174, v181 offset:1536
	ds_read_b32 v175, v181 offset:1792
	s_waitcnt lgkmcnt(0)
	v_lshl_add_u64 v[176:177], v[60:61], 0, v[160:161]
	global_atomic_add_f32 v[176:177], v168, off offset:0
	v_lshl_add_u64 v[178:179], v[60:61], 0, v[162:163]
	global_atomic_add_f32 v[178:179], v169, off offset:0
	v_lshl_add_u64 v[176:177], v[60:61], 0, v[164:165]
	global_atomic_add_f32 v[176:177], v170, off offset:0
	v_lshl_add_u64 v[178:179], v[60:61], 0, v[166:167]
	global_atomic_add_f32 v[178:179], v171, off offset:0
	v_lshl_add_u64 v[176:177], v[60:61], 0, v[160:161]
	global_atomic_add_f32 v[176:177], v172, off offset:64
	v_lshl_add_u64 v[178:179], v[60:61], 0, v[162:163]
	global_atomic_add_f32 v[178:179], v173, off offset:64
	v_lshl_add_u64 v[176:177], v[60:61], 0, v[164:165]
	global_atomic_add_f32 v[176:177], v174, off offset:64
	v_lshl_add_u64 v[178:179], v[60:61], 0, v[166:167]
	global_atomic_add_f32 v[178:179], v175, off offset:64
	v_lshlrev_b64 v[50:51], 12, v[132:133]
	v_lshl_add_u64 v[50:51], s[8:9], 0, v[50:51]
	v_lshl_add_u64 v[50:51], v[50:51], 0, v[146:147]
	ds_write_b128 v180, v[46:49] offset:0
	ds_write_b128 v180, v[42:45] offset:1024
	s_nop 1
	s_waitcnt lgkmcnt(0)
	ds_read_b32 v168, v181 offset:0
	ds_read_b32 v169, v181 offset:256
	ds_read_b32 v170, v181 offset:512
	ds_read_b32 v171, v181 offset:768
	ds_read_b32 v172, v181 offset:1024
	ds_read_b32 v173, v181 offset:1280
	ds_read_b32 v174, v181 offset:1536
	ds_read_b32 v175, v181 offset:1792
	s_waitcnt lgkmcnt(0)
	v_lshl_add_u64 v[176:177], v[50:51], 0, v[160:161]
	global_atomic_add_f32 v[176:177], v168, off offset:0
	v_lshl_add_u64 v[178:179], v[50:51], 0, v[162:163]
	global_atomic_add_f32 v[178:179], v169, off offset:0
	v_lshl_add_u64 v[176:177], v[50:51], 0, v[164:165]
	global_atomic_add_f32 v[176:177], v170, off offset:0
	v_lshl_add_u64 v[178:179], v[50:51], 0, v[166:167]
	global_atomic_add_f32 v[178:179], v171, off offset:0
	v_lshl_add_u64 v[176:177], v[50:51], 0, v[160:161]
	global_atomic_add_f32 v[176:177], v172, off offset:64
	v_lshl_add_u64 v[178:179], v[50:51], 0, v[162:163]
	global_atomic_add_f32 v[178:179], v173, off offset:64
	v_lshl_add_u64 v[176:177], v[50:51], 0, v[164:165]
	global_atomic_add_f32 v[176:177], v174, off offset:64
	v_lshl_add_u64 v[178:179], v[50:51], 0, v[166:167]
	global_atomic_add_f32 v[178:179], v175, off offset:64
	v_lshlrev_b64 v[42:43], 12, v[130:131]
	v_lshl_add_u64 v[42:43], s[8:9], 0, v[42:43]
	v_lshl_add_u64 v[42:43], v[42:43], 0, v[146:147]
	ds_write_b128 v180, v[38:41] offset:0
	ds_write_b128 v180, v[30:33] offset:1024
	s_nop 1
	s_waitcnt lgkmcnt(0)
	ds_read_b32 v168, v181 offset:0
	ds_read_b32 v169, v181 offset:256
	ds_read_b32 v170, v181 offset:512
	ds_read_b32 v171, v181 offset:768
	ds_read_b32 v172, v181 offset:1024
	ds_read_b32 v173, v181 offset:1280
	ds_read_b32 v174, v181 offset:1536
	ds_read_b32 v175, v181 offset:1792
	s_waitcnt lgkmcnt(0)
	v_lshl_add_u64 v[176:177], v[42:43], 0, v[160:161]
	global_atomic_add_f32 v[176:177], v168, off offset:0
	v_lshl_add_u64 v[178:179], v[42:43], 0, v[162:163]
	global_atomic_add_f32 v[178:179], v169, off offset:0
	v_lshl_add_u64 v[176:177], v[42:43], 0, v[164:165]
	global_atomic_add_f32 v[176:177], v170, off offset:0
	v_lshl_add_u64 v[178:179], v[42:43], 0, v[166:167]
	global_atomic_add_f32 v[178:179], v171, off offset:0
	v_lshl_add_u64 v[176:177], v[42:43], 0, v[160:161]
	global_atomic_add_f32 v[176:177], v172, off offset:64
	v_lshl_add_u64 v[178:179], v[42:43], 0, v[162:163]
	global_atomic_add_f32 v[178:179], v173, off offset:64
	v_lshl_add_u64 v[176:177], v[42:43], 0, v[164:165]
	global_atomic_add_f32 v[176:177], v174, off offset:64
	v_lshl_add_u64 v[178:179], v[42:43], 0, v[166:167]
	global_atomic_add_f32 v[178:179], v175, off offset:64
	ds_write_b128 v180, v[34:37] offset:0
	ds_write_b128 v180, v[26:29] offset:1024
	s_nop 1
	s_waitcnt lgkmcnt(0)
	ds_read_b32 v168, v181 offset:0
	ds_read_b32 v169, v181 offset:256
	ds_read_b32 v170, v181 offset:512
	ds_read_b32 v171, v181 offset:768
	ds_read_b32 v172, v181 offset:1024
	ds_read_b32 v173, v181 offset:1280
	ds_read_b32 v174, v181 offset:1536
	ds_read_b32 v175, v181 offset:1792
	s_waitcnt lgkmcnt(0)
	v_lshl_add_u64 v[176:177], v[58:59], 0, v[160:161]
	global_atomic_add_f32 v[176:177], v168, off offset:512
	v_lshl_add_u64 v[178:179], v[58:59], 0, v[162:163]
	global_atomic_add_f32 v[178:179], v169, off offset:512
	v_lshl_add_u64 v[176:177], v[58:59], 0, v[164:165]
	global_atomic_add_f32 v[176:177], v170, off offset:512
	v_lshl_add_u64 v[178:179], v[58:59], 0, v[166:167]
	global_atomic_add_f32 v[178:179], v171, off offset:512
	v_lshl_add_u64 v[176:177], v[58:59], 0, v[160:161]
	global_atomic_add_f32 v[176:177], v172, off offset:576
	v_lshl_add_u64 v[178:179], v[58:59], 0, v[162:163]
	global_atomic_add_f32 v[178:179], v173, off offset:576
	v_lshl_add_u64 v[176:177], v[58:59], 0, v[164:165]
	global_atomic_add_f32 v[176:177], v174, off offset:576
	v_lshl_add_u64 v[178:179], v[58:59], 0, v[166:167]
	global_atomic_add_f32 v[178:179], v175, off offset:576
	ds_write_b128 v180, v[22:25] offset:0
	ds_write_b128 v180, v[18:21] offset:1024
	s_nop 1
	s_waitcnt lgkmcnt(0)
	ds_read_b32 v168, v181 offset:0
	ds_read_b32 v169, v181 offset:256
	ds_read_b32 v170, v181 offset:512
	ds_read_b32 v171, v181 offset:768
	ds_read_b32 v172, v181 offset:1024
	ds_read_b32 v173, v181 offset:1280
	ds_read_b32 v174, v181 offset:1536
	ds_read_b32 v175, v181 offset:1792
	s_waitcnt lgkmcnt(0)
	v_lshl_add_u64 v[176:177], v[60:61], 0, v[160:161]
	global_atomic_add_f32 v[176:177], v168, off offset:512
	v_lshl_add_u64 v[178:179], v[60:61], 0, v[162:163]
	global_atomic_add_f32 v[178:179], v169, off offset:512
	v_lshl_add_u64 v[176:177], v[60:61], 0, v[164:165]
	global_atomic_add_f32 v[176:177], v170, off offset:512
	v_lshl_add_u64 v[178:179], v[60:61], 0, v[166:167]
	global_atomic_add_f32 v[178:179], v171, off offset:512
	v_lshl_add_u64 v[176:177], v[60:61], 0, v[160:161]
	global_atomic_add_f32 v[176:177], v172, off offset:576
	v_lshl_add_u64 v[178:179], v[60:61], 0, v[162:163]
	global_atomic_add_f32 v[178:179], v173, off offset:576
	v_lshl_add_u64 v[176:177], v[60:61], 0, v[164:165]
	global_atomic_add_f32 v[176:177], v174, off offset:576
	v_lshl_add_u64 v[178:179], v[60:61], 0, v[166:167]
	global_atomic_add_f32 v[178:179], v175, off offset:576
	ds_write_b128 v180, v[14:17] offset:0
	ds_write_b128 v180, v[10:13] offset:1024
	s_nop 1
	s_waitcnt lgkmcnt(0)
	ds_read_b32 v168, v181 offset:0
	ds_read_b32 v169, v181 offset:256
	ds_read_b32 v170, v181 offset:512
	ds_read_b32 v171, v181 offset:768
	ds_read_b32 v172, v181 offset:1024
	ds_read_b32 v173, v181 offset:1280
	ds_read_b32 v174, v181 offset:1536
	ds_read_b32 v175, v181 offset:1792
	s_waitcnt lgkmcnt(0)
	v_lshl_add_u64 v[176:177], v[50:51], 0, v[160:161]
	global_atomic_add_f32 v[176:177], v168, off offset:512
	v_lshl_add_u64 v[178:179], v[50:51], 0, v[162:163]
	global_atomic_add_f32 v[178:179], v169, off offset:512
	v_lshl_add_u64 v[176:177], v[50:51], 0, v[164:165]
	global_atomic_add_f32 v[176:177], v170, off offset:512
	v_lshl_add_u64 v[178:179], v[50:51], 0, v[166:167]
	global_atomic_add_f32 v[178:179], v171, off offset:512
	v_lshl_add_u64 v[176:177], v[50:51], 0, v[160:161]
	global_atomic_add_f32 v[176:177], v172, off offset:576
	v_lshl_add_u64 v[178:179], v[50:51], 0, v[162:163]
	global_atomic_add_f32 v[178:179], v173, off offset:576
	v_lshl_add_u64 v[176:177], v[50:51], 0, v[164:165]
	global_atomic_add_f32 v[176:177], v174, off offset:576
	v_lshl_add_u64 v[178:179], v[50:51], 0, v[166:167]
	global_atomic_add_f32 v[178:179], v175, off offset:576
	ds_write_b128 v180, v[6:9] offset:0
	ds_write_b128 v180, v[2:5] offset:1024
	s_nop 1
	s_waitcnt lgkmcnt(0)
	ds_read_b32 v168, v181 offset:0
	ds_read_b32 v169, v181 offset:256
	ds_read_b32 v170, v181 offset:512
	ds_read_b32 v171, v181 offset:768
	ds_read_b32 v172, v181 offset:1024
	ds_read_b32 v173, v181 offset:1280
	ds_read_b32 v174, v181 offset:1536
	ds_read_b32 v175, v181 offset:1792
	s_waitcnt lgkmcnt(0)
	v_lshl_add_u64 v[176:177], v[42:43], 0, v[160:161]
	global_atomic_add_f32 v[176:177], v168, off offset:512
	v_lshl_add_u64 v[178:179], v[42:43], 0, v[162:163]
	global_atomic_add_f32 v[178:179], v169, off offset:512
	v_lshl_add_u64 v[176:177], v[42:43], 0, v[164:165]
	global_atomic_add_f32 v[176:177], v170, off offset:512
	v_lshl_add_u64 v[178:179], v[42:43], 0, v[166:167]
	global_atomic_add_f32 v[178:179], v171, off offset:512
	v_lshl_add_u64 v[176:177], v[42:43], 0, v[160:161]
	global_atomic_add_f32 v[176:177], v172, off offset:576
	v_lshl_add_u64 v[178:179], v[42:43], 0, v[162:163]
	global_atomic_add_f32 v[178:179], v173, off offset:576
	v_lshl_add_u64 v[176:177], v[42:43], 0, v[164:165]
	global_atomic_add_f32 v[176:177], v174, off offset:576
	v_lshl_add_u64 v[178:179], v[42:43], 0, v[166:167]
	global_atomic_add_f32 v[178:179], v175, off offset:576

.LBB0_1604:
	s_andn2_b64 vcc, exec, s[12:13]
	s_cbranch_vccnz .LBB0_1606
	v_and_b32_e32 v182, 15, v219
	v_lshrrev_b32_e32 v183, 4, v219
	v_lshrrev_b32_e32 v180, 6, v211
	v_lshlrev_b32_e32 v180, 11, v180
	v_lshl_add_u32 v181, v183, 6, v180
	v_lshl_add_u32 v181, v182, 2, v181
	v_lshl_add_u32 v180, v182, 6, v180
	v_lshl_add_u32 v180, v183, 4, v180
	v_sub_u32_e32 v184, v183, v182
	v_lshlrev_b32_e32 v184, 12, v184
	v_lshlrev_b32_e32 v185, 2, v183
	v_sub_u32_e32 v185, v182, v185
	v_lshlrev_b32_e32 v185, 2, v185
	v_add_u32_e32 v184, v184, v185
	v_mov_b32_e32 v160, v184
	v_ashrrev_i32_e32 v161, 31, v160
	v_add_u32_e32 v162, 0x4000, v184
	v_ashrrev_i32_e32 v163, 31, v162
	v_add_u32_e32 v164, 0x8000, v184
	v_ashrrev_i32_e32 v165, 31, v164
	v_add_u32_e32 v166, 0xc000, v184
	v_ashrrev_i32_e32 v167, 31, v166
	v_lshlrev_b64 v[130:131], 12, v[150:151]
	v_lshl_add_u64 v[130:131], s[4:5], 0, v[130:131]
	v_lshlrev_b64 v[132:133], 2, v[152:153]
	v_lshl_add_u64 v[130:131], v[130:131], 0, v[132:133]
	s_waitcnt vmcnt(0)
	ds_write_b128 v180, v[126:129] offset:0
	ds_write_b128 v180, v[122:125] offset:1024
	s_nop 1
	s_waitcnt lgkmcnt(0)
	ds_read_b32 v168, v181 offset:0
	ds_read_b32 v169, v181 offset:256
	ds_read_b32 v170, v181 offset:512
	ds_read_b32 v171, v181 offset:768
	ds_read_b32 v172, v181 offset:1024
	ds_read_b32 v173, v181 offset:1280
	ds_read_b32 v174, v181 offset:1536
	ds_read_b32 v175, v181 offset:1792
	s_waitcnt lgkmcnt(0)
	v_lshl_add_u64 v[176:177], v[130:131], 0, v[160:161]
	global_atomic_add_f32 v[176:177], v168, off offset:0
	v_lshl_add_u64 v[178:179], v[130:131], 0, v[162:163]
	global_atomic_add_f32 v[178:179], v169, off offset:0
	v_lshl_add_u64 v[176:177], v[130:131], 0, v[164:165]
	global_atomic_add_f32 v[176:177], v170, off offset:0
	v_lshl_add_u64 v[178:179], v[130:131], 0, v[166:167]
	global_atomic_add_f32 v[178:179], v171, off offset:0
	v_lshl_add_u64 v[176:177], v[130:131], 0, v[160:161]
	global_atomic_add_f32 v[176:177], v172, off offset:64
	v_lshl_add_u64 v[178:179], v[130:131], 0, v[162:163]
	global_atomic_add_f32 v[178:179], v173, off offset:64
	v_lshl_add_u64 v[176:177], v[130:131], 0, v[164:165]
	global_atomic_add_f32 v[176:177], v174, off offset:64
	v_lshl_add_u64 v[178:179], v[130:131], 0, v[166:167]
	global_atomic_add_f32 v[178:179], v175, off offset:64
	v_lshlrev_b64 v[122:123], 12, v[148:149]
	v_lshl_add_u64 v[122:123], s[4:5], 0, v[122:123]
	v_lshl_add_u64 v[122:123], v[122:123], 0, v[132:133]
	ds_write_b128 v180, v[118:121] offset:0
	ds_write_b128 v180, v[114:117] offset:1024
	s_nop 1
	s_waitcnt lgkmcnt(0)
	ds_read_b32 v168, v181 offset:0
	ds_read_b32 v169, v181 offset:256
	ds_read_b32 v170, v181 offset:512
	ds_read_b32 v171, v181 offset:768
	ds_read_b32 v172, v181 offset:1024
	ds_read_b32 v173, v181 offset:1280
	ds_read_b32 v174, v181 offset:1536
	ds_read_b32 v175, v181 offset:1792
	s_waitcnt lgkmcnt(0)
	v_lshl_add_u64 v[176:177], v[122:123], 0, v[160:161]
	global_atomic_add_f32 v[176:177], v168, off offset:0
	v_lshl_add_u64 v[178:179], v[122:123], 0, v[162:163]
	global_atomic_add_f32 v[178:179], v169, off offset:0
	v_lshl_add_u64 v[176:177], v[122:123], 0, v[164:165]
	global_atomic_add_f32 v[176:177], v170, off offset:0
	v_lshl_add_u64 v[178:179], v[122:123], 0, v[166:167]
	global_atomic_add_f32 v[178:179], v171, off offset:0
	v_lshl_add_u64 v[176:177], v[122:123], 0, v[160:161]
	global_atomic_add_f32 v[176:177], v172, off offset:64
	v_lshl_add_u64 v[178:179], v[122:123], 0, v[162:163]
	global_atomic_add_f32 v[178:179], v173, off offset:64
	v_lshl_add_u64 v[176:177], v[122:123], 0, v[164:165]
	global_atomic_add_f32 v[176:177], v174, off offset:64
	v_lshl_add_u64 v[178:179], v[122:123], 0, v[166:167]
	global_atomic_add_f32 v[178:179], v175, off offset:64
	v_lshlrev_b64 v[114:115], 12, v[144:145]
	v_lshl_add_u64 v[114:115], s[4:5], 0, v[114:115]
	v_lshl_add_u64 v[114:115], v[114:115], 0, v[132:133]
	ds_write_b128 v180, v[110:113] offset:0
	ds_write_b128 v180, v[106:109] offset:1024
	s_nop 1
	s_waitcnt lgkmcnt(0)
	ds_read_b32 v168, v181 offset:0
	ds_read_b32 v169, v181 offset:256
	ds_read_b32 v170, v181 offset:512
	ds_read_b32 v171, v181 offset:768
	ds_read_b32 v172, v181 offset:1024
	ds_read_b32 v173, v181 offset:1280
	ds_read_b32 v174, v181 offset:1536
	ds_read_b32 v175, v181 offset:1792
	s_waitcnt lgkmcnt(0)
	v_lshl_add_u64 v[176:177], v[114:115], 0, v[160:161]
	global_atomic_add_f32 v[176:177], v168, off offset:0
	v_lshl_add_u64 v[178:179], v[114:115], 0, v[162:163]
	global_atomic_add_f32 v[178:179], v169, off offset:0
	v_lshl_add_u64 v[176:177], v[114:115], 0, v[164:165]
	global_atomic_add_f32 v[176:177], v170, off offset:0
	v_lshl_add_u64 v[178:179], v[114:115], 0, v[166:167]
	global_atomic_add_f32 v[178:179], v171, off offset:0
	v_lshl_add_u64 v[176:177], v[114:115], 0, v[160:161]
	global_atomic_add_f32 v[176:177], v172, off offset:64
	v_lshl_add_u64 v[178:179], v[114:115], 0, v[162:163]
	global_atomic_add_f32 v[178:179], v173, off offset:64
	v_lshl_add_u64 v[176:177], v[114:115], 0, v[164:165]
	global_atomic_add_f32 v[176:177], v174, off offset:64
	v_lshl_add_u64 v[178:179], v[114:115], 0, v[166:167]
	global_atomic_add_f32 v[178:179], v175, off offset:64
	v_lshlrev_b64 v[106:107], 12, v[142:143]
	v_lshl_add_u64 v[106:107], s[4:5], 0, v[106:107]
	v_lshl_add_u64 v[106:107], v[106:107], 0, v[132:133]
	ds_write_b128 v180, v[86:89] offset:0
	ds_write_b128 v180, v[74:77] offset:1024
	s_nop 1
	s_waitcnt lgkmcnt(0)
	ds_read_b32 v168, v181 offset:0
	ds_read_b32 v169, v181 offset:256
	ds_read_b32 v170, v181 offset:512
	ds_read_b32 v171, v181 offset:768
	ds_read_b32 v172, v181 offset:1024
	ds_read_b32 v173, v181 offset:1280
	ds_read_b32 v174, v181 offset:1536
	ds_read_b32 v175, v181 offset:1792
	s_waitcnt lgkmcnt(0)
	v_lshl_add_u64 v[176:177], v[106:107], 0, v[160:161]
	global_atomic_add_f32 v[176:177], v168, off offset:0
	v_lshl_add_u64 v[178:179], v[106:107], 0, v[162:163]
	global_atomic_add_f32 v[178:179], v169, off offset:0
	v_lshl_add_u64 v[176:177], v[106:107], 0, v[164:165]
	global_atomic_add_f32 v[176:177], v170, off offset:0
	v_lshl_add_u64 v[178:179], v[106:107], 0, v[166:167]
	global_atomic_add_f32 v[178:179], v171, off offset:0
	v_lshl_add_u64 v[176:177], v[106:107], 0, v[160:161]
	global_atomic_add_f32 v[176:177], v172, off offset:64
	v_lshl_add_u64 v[178:179], v[106:107], 0, v[162:163]
	global_atomic_add_f32 v[178:179], v173, off offset:64
	v_lshl_add_u64 v[176:177], v[106:107], 0, v[164:165]
	global_atomic_add_f32 v[176:177], v174, off offset:64
	v_lshl_add_u64 v[178:179], v[106:107], 0, v[166:167]
	global_atomic_add_f32 v[178:179], v175, off offset:64
	ds_write_b128 v180, v[102:105] offset:0
	ds_write_b128 v180, v[98:101] offset:1024
	s_nop 1
	s_waitcnt lgkmcnt(0)
	ds_read_b32 v168, v181 offset:0
	ds_read_b32 v169, v181 offset:256
	ds_read_b32 v170, v181 offset:512
	ds_read_b32 v171, v181 offset:768
	ds_read_b32 v172, v181 offset:1024
	ds_read_b32 v173, v181 offset:1280
	ds_read_b32 v174, v181 offset:1536
	ds_read_b32 v175, v181 offset:1792
	s_waitcnt lgkmcnt(0)
	v_lshl_add_u64 v[176:177], v[130:131], 0, v[160:161]
	global_atomic_add_f32 v[176:177], v168, off offset:512
	v_lshl_add_u64 v[178:179], v[130:131], 0, v[162:163]
	global_atomic_add_f32 v[178:179], v169, off offset:512
	v_lshl_add_u64 v[176:177], v[130:131], 0, v[164:165]
	global_atomic_add_f32 v[176:177], v170, off offset:512
	v_lshl_add_u64 v[178:179], v[130:131], 0, v[166:167]
	global_atomic_add_f32 v[178:179], v171, off offset:512
	v_lshl_add_u64 v[176:177], v[130:131], 0, v[160:161]
	global_atomic_add_f32 v[176:177], v172, off offset:576
	v_lshl_add_u64 v[178:179], v[130:131], 0, v[162:163]
	global_atomic_add_f32 v[178:179], v173, off offset:576
	v_lshl_add_u64 v[176:177], v[130:131], 0, v[164:165]
	global_atomic_add_f32 v[176:177], v174, off offset:576
	v_lshl_add_u64 v[178:179], v[130:131], 0, v[166:167]
	global_atomic_add_f32 v[178:179], v175, off offset:576
	ds_write_b128 v180, v[94:97] offset:0
	ds_write_b128 v180, v[90:93] offset:1024
	s_nop 1
	s_waitcnt lgkmcnt(0)
	ds_read_b32 v168, v181 offset:0
	ds_read_b32 v169, v181 offset:256
	ds_read_b32 v170, v181 offset:512
	ds_read_b32 v171, v181 offset:768
	ds_read_b32 v172, v181 offset:1024
	ds_read_b32 v173, v181 offset:1280
	ds_read_b32 v174, v181 offset:1536
	ds_read_b32 v175, v181 offset:1792
	s_waitcnt lgkmcnt(0)
	v_lshl_add_u64 v[176:177], v[122:123], 0, v[160:161]
	global_atomic_add_f32 v[176:177], v168, off offset:512
	v_lshl_add_u64 v[178:179], v[122:123], 0, v[162:163]
	global_atomic_add_f32 v[178:179], v169, off offset:512
	v_lshl_add_u64 v[176:177], v[122:123], 0, v[164:165]
	global_atomic_add_f32 v[176:177], v170, off offset:512
	v_lshl_add_u64 v[178:179], v[122:123], 0, v[166:167]
	global_atomic_add_f32 v[178:179], v171, off offset:512
	v_lshl_add_u64 v[176:177], v[122:123], 0, v[160:161]
	global_atomic_add_f32 v[176:177], v172, off offset:576
	v_lshl_add_u64 v[178:179], v[122:123], 0, v[162:163]
	global_atomic_add_f32 v[178:179], v173, off offset:576
	v_lshl_add_u64 v[176:177], v[122:123], 0, v[164:165]
	global_atomic_add_f32 v[176:177], v174, off offset:576
	v_lshl_add_u64 v[178:179], v[122:123], 0, v[166:167]
	global_atomic_add_f32 v[178:179], v175, off offset:576
	ds_write_b128 v180, v[78:81] offset:0
	ds_write_b128 v180, v[66:69] offset:1024
	s_nop 1
	s_waitcnt lgkmcnt(0)
	ds_read_b32 v168, v181 offset:0
	ds_read_b32 v169, v181 offset:256
	ds_read_b32 v170, v181 offset:512
	ds_read_b32 v171, v181 offset:768
	ds_read_b32 v172, v181 offset:1024
	ds_read_b32 v173, v181 offset:1280
	ds_read_b32 v174, v181 offset:1536
	ds_read_b32 v175, v181 offset:1792
	s_waitcnt lgkmcnt(0)
	v_lshl_add_u64 v[176:177], v[114:115], 0, v[160:161]
	global_atomic_add_f32 v[176:177], v168, off offset:512
	v_lshl_add_u64 v[178:179], v[114:115], 0, v[162:163]
	global_atomic_add_f32 v[178:179], v169, off offset:512
	v_lshl_add_u64 v[176:177], v[114:115], 0, v[164:165]
	global_atomic_add_f32 v[176:177], v170, off offset:512
	v_lshl_add_u64 v[178:179], v[114:115], 0, v[166:167]
	global_atomic_add_f32 v[178:179], v171, off offset:512
	v_lshl_add_u64 v[176:177], v[114:115], 0, v[160:161]
	global_atomic_add_f32 v[176:177], v172, off offset:576
	v_lshl_add_u64 v[178:179], v[114:115], 0, v[162:163]
	global_atomic_add_f32 v[178:179], v173, off offset:576
	v_lshl_add_u64 v[176:177], v[114:115], 0, v[164:165]
	global_atomic_add_f32 v[176:177], v174, off offset:576
	v_lshl_add_u64 v[178:179], v[114:115], 0, v[166:167]
	global_atomic_add_f32 v[178:179], v175, off offset:576
	ds_write_b128 v180, v[62:65] offset:0
	ds_write_b128 v180, v[58:61] offset:1024
	s_nop 1
	s_waitcnt lgkmcnt(0)
	ds_read_b32 v168, v181 offset:0
	ds_read_b32 v169, v181 offset:256
	ds_read_b32 v170, v181 offset:512
	ds_read_b32 v171, v181 offset:768
	ds_read_b32 v172, v181 offset:1024
	ds_read_b32 v173, v181 offset:1280
	ds_read_b32 v174, v181 offset:1536
	ds_read_b32 v175, v181 offset:1792
	s_waitcnt lgkmcnt(0)
	v_lshl_add_u64 v[176:177], v[106:107], 0, v[160:161]
	global_atomic_add_f32 v[176:177], v168, off offset:512
	v_lshl_add_u64 v[178:179], v[106:107], 0, v[162:163]
	global_atomic_add_f32 v[178:179], v169, off offset:512
	v_lshl_add_u64 v[176:177], v[106:107], 0, v[164:165]
	global_atomic_add_f32 v[176:177], v170, off offset:512
	v_lshl_add_u64 v[178:179], v[106:107], 0, v[166:167]
	global_atomic_add_f32 v[178:179], v171, off offset:512
	v_lshl_add_u64 v[176:177], v[106:107], 0, v[160:161]
	global_atomic_add_f32 v[176:177], v172, off offset:576
	v_lshl_add_u64 v[178:179], v[106:107], 0, v[162:163]
	global_atomic_add_f32 v[178:179], v173, off offset:576
	v_lshl_add_u64 v[176:177], v[106:107], 0, v[164:165]
	global_atomic_add_f32 v[176:177], v174, off offset:576
	v_lshl_add_u64 v[178:179], v[106:107], 0, v[166:167]
	global_atomic_add_f32 v[178:179], v175, off offset:576
	v_lshlrev_b64 v[58:59], 12, v[140:141]
	v_lshl_add_u64 v[58:59], s[4:5], 0, v[58:59]
	v_lshlrev_b64 v[60:61], 12, v[138:139]
	v_lshl_add_u64 v[58:59], v[58:59], 0, v[132:133]
	v_lshl_add_u64 v[60:61], s[4:5], 0, v[60:61]
	ds_write_b128 v180, v[82:85] offset:0
	ds_write_b128 v180, v[70:73] offset:1024
	s_nop 1
	s_waitcnt lgkmcnt(0)
	ds_read_b32 v168, v181 offset:0
	ds_read_b32 v169, v181 offset:256
	ds_read_b32 v170, v181 offset:512
	ds_read_b32 v171, v181 offset:768
	ds_read_b32 v172, v181 offset:1024
	ds_read_b32 v173, v181 offset:1280
	ds_read_b32 v174, v181 offset:1536
	ds_read_b32 v175, v181 offset:1792
	s_waitcnt lgkmcnt(0)
	v_lshl_add_u64 v[176:177], v[58:59], 0, v[160:161]
	global_atomic_add_f32 v[176:177], v168, off offset:0
	v_lshl_add_u64 v[178:179], v[58:59], 0, v[162:163]
	global_atomic_add_f32 v[178:179], v169, off offset:0
	v_lshl_add_u64 v[176:177], v[58:59], 0, v[164:165]
	global_atomic_add_f32 v[176:177], v170, off offset:0
	v_lshl_add_u64 v[178:179], v[58:59], 0, v[166:167]
	global_atomic_add_f32 v[178:179], v171, off offset:0
	v_lshl_add_u64 v[176:177], v[58:59], 0, v[160:161]
	global_atomic_add_f32 v[176:177], v172, off offset:64
	v_lshl_add_u64 v[178:179], v[58:59], 0, v[162:163]
	global_atomic_add_f32 v[178:179], v173, off offset:64
	v_lshl_add_u64 v[176:177], v[58:59], 0, v[164:165]
	global_atomic_add_f32 v[176:177], v174, off offset:64
	v_lshl_add_u64 v[178:179], v[58:59], 0, v[166:167]
	global_atomic_add_f32 v[178:179], v175, off offset:64
	v_lshl_add_u64 v[60:61], v[60:61], 0, v[132:133]
	ds_write_b128 v180, v[54:57] offset:0
	ds_write_b128 v180, v[50:53] offset:1024
	s_nop 1
	s_waitcnt lgkmcnt(0)
	ds_read_b32 v168, v181 offset:0
	ds_read_b32 v169, v181 offset:256
	ds_read_b32 v170, v181 offset:512
	ds_read_b32 v171, v181 offset:768
	ds_read_b32 v172, v181 offset:1024
	ds_read_b32 v173, v181 offset:1280
	ds_read_b32 v174, v181 offset:1536
	ds_read_b32 v175, v181 offset:1792
	s_waitcnt lgkmcnt(0)
	v_lshl_add_u64 v[176:177], v[60:61], 0, v[160:161]
	global_atomic_add_f32 v[176:177], v168, off offset:0
	v_lshl_add_u64 v[178:179], v[60:61], 0, v[162:163]
	global_atomic_add_f32 v[178:179], v169, off offset:0
	v_lshl_add_u64 v[176:177], v[60:61], 0, v[164:165]
	global_atomic_add_f32 v[176:177], v170, off offset:0
	v_lshl_add_u64 v[178:179], v[60:61], 0, v[166:167]
	global_atomic_add_f32 v[178:179], v171, off offset:0
	v_lshl_add_u64 v[176:177], v[60:61], 0, v[160:161]
	global_atomic_add_f32 v[176:177], v172, off offset:64
	v_lshl_add_u64 v[178:179], v[60:61], 0, v[162:163]
	global_atomic_add_f32 v[178:179], v173, off offset:64
	v_lshl_add_u64 v[176:177], v[60:61], 0, v[164:165]
	global_atomic_add_f32 v[176:177], v174, off offset:64
	v_lshl_add_u64 v[178:179], v[60:61], 0, v[166:167]
	global_atomic_add_f32 v[178:179], v175, off offset:64
	v_lshlrev_b64 v[50:51], 12, v[136:137]
	v_lshl_add_u64 v[50:51], s[4:5], 0, v[50:51]
	v_lshl_add_u64 v[50:51], v[50:51], 0, v[132:133]
	ds_write_b128 v180, v[46:49] offset:0
	ds_write_b128 v180, v[42:45] offset:1024
	s_nop 1
	s_waitcnt lgkmcnt(0)
	ds_read_b32 v168, v181 offset:0
	ds_read_b32 v169, v181 offset:256
	ds_read_b32 v170, v181 offset:512
	ds_read_b32 v171, v181 offset:768
	ds_read_b32 v172, v181 offset:1024
	ds_read_b32 v173, v181 offset:1280
	ds_read_b32 v174, v181 offset:1536
	ds_read_b32 v175, v181 offset:1792
	s_waitcnt lgkmcnt(0)
	v_lshl_add_u64 v[176:177], v[50:51], 0, v[160:161]
	global_atomic_add_f32 v[176:177], v168, off offset:0
	v_lshl_add_u64 v[178:179], v[50:51], 0, v[162:163]
	global_atomic_add_f32 v[178:179], v169, off offset:0
	v_lshl_add_u64 v[176:177], v[50:51], 0, v[164:165]
	global_atomic_add_f32 v[176:177], v170, off offset:0
	v_lshl_add_u64 v[178:179], v[50:51], 0, v[166:167]
	global_atomic_add_f32 v[178:179], v171, off offset:0
	v_lshl_add_u64 v[176:177], v[50:51], 0, v[160:161]
	global_atomic_add_f32 v[176:177], v172, off offset:64
	v_lshl_add_u64 v[178:179], v[50:51], 0, v[162:163]
	global_atomic_add_f32 v[178:179], v173, off offset:64
	v_lshl_add_u64 v[176:177], v[50:51], 0, v[164:165]
	global_atomic_add_f32 v[176:177], v174, off offset:64
	v_lshl_add_u64 v[178:179], v[50:51], 0, v[166:167]
	global_atomic_add_f32 v[178:179], v175, off offset:64
	v_lshlrev_b64 v[42:43], 12, v[134:135]
	v_lshl_add_u64 v[42:43], s[4:5], 0, v[42:43]
	v_lshl_add_u64 v[42:43], v[42:43], 0, v[132:133]
	ds_write_b128 v180, v[38:41] offset:0
	ds_write_b128 v180, v[30:33] offset:1024
	s_nop 1
	s_waitcnt lgkmcnt(0)
	ds_read_b32 v168, v181 offset:0
	ds_read_b32 v169, v181 offset:256
	ds_read_b32 v170, v181 offset:512
	ds_read_b32 v171, v181 offset:768
	ds_read_b32 v172, v181 offset:1024
	ds_read_b32 v173, v181 offset:1280
	ds_read_b32 v174, v181 offset:1536
	ds_read_b32 v175, v181 offset:1792
	s_waitcnt lgkmcnt(0)
	v_lshl_add_u64 v[176:177], v[42:43], 0, v[160:161]
	global_atomic_add_f32 v[176:177], v168, off offset:0
	v_lshl_add_u64 v[178:179], v[42:43], 0, v[162:163]
	global_atomic_add_f32 v[178:179], v169, off offset:0
	v_lshl_add_u64 v[176:177], v[42:43], 0, v[164:165]
	global_atomic_add_f32 v[176:177], v170, off offset:0
	v_lshl_add_u64 v[178:179], v[42:43], 0, v[166:167]
	global_atomic_add_f32 v[178:179], v171, off offset:0
	v_lshl_add_u64 v[176:177], v[42:43], 0, v[160:161]
	global_atomic_add_f32 v[176:177], v172, off offset:64
	v_lshl_add_u64 v[178:179], v[42:43], 0, v[162:163]
	global_atomic_add_f32 v[178:179], v173, off offset:64
	v_lshl_add_u64 v[176:177], v[42:43], 0, v[164:165]
	global_atomic_add_f32 v[176:177], v174, off offset:64
	v_lshl_add_u64 v[178:179], v[42:43], 0, v[166:167]
	global_atomic_add_f32 v[178:179], v175, off offset:64
	ds_write_b128 v180, v[34:37] offset:0
	ds_write_b128 v180, v[26:29] offset:1024
	s_nop 1
	s_waitcnt lgkmcnt(0)
	ds_read_b32 v168, v181 offset:0
	ds_read_b32 v169, v181 offset:256
	ds_read_b32 v170, v181 offset:512
	ds_read_b32 v171, v181 offset:768
	ds_read_b32 v172, v181 offset:1024
	ds_read_b32 v173, v181 offset:1280
	ds_read_b32 v174, v181 offset:1536
	ds_read_b32 v175, v181 offset:1792
	s_waitcnt lgkmcnt(0)
	v_lshl_add_u64 v[176:177], v[58:59], 0, v[160:161]
	global_atomic_add_f32 v[176:177], v168, off offset:512
	v_lshl_add_u64 v[178:179], v[58:59], 0, v[162:163]
	global_atomic_add_f32 v[178:179], v169, off offset:512
	v_lshl_add_u64 v[176:177], v[58:59], 0, v[164:165]
	global_atomic_add_f32 v[176:177], v170, off offset:512
	v_lshl_add_u64 v[178:179], v[58:59], 0, v[166:167]
	global_atomic_add_f32 v[178:179], v171, off offset:512
	v_lshl_add_u64 v[176:177], v[58:59], 0, v[160:161]
	global_atomic_add_f32 v[176:177], v172, off offset:576
	v_lshl_add_u64 v[178:179], v[58:59], 0, v[162:163]
	global_atomic_add_f32 v[178:179], v173, off offset:576
	v_lshl_add_u64 v[176:177], v[58:59], 0, v[164:165]
	global_atomic_add_f32 v[176:177], v174, off offset:576
	v_lshl_add_u64 v[178:179], v[58:59], 0, v[166:167]
	global_atomic_add_f32 v[178:179], v175, off offset:576
	ds_write_b128 v180, v[22:25] offset:0
	ds_write_b128 v180, v[18:21] offset:1024
	s_nop 1
	s_waitcnt lgkmcnt(0)
	ds_read_b32 v168, v181 offset:0
	ds_read_b32 v169, v181 offset:256
	ds_read_b32 v170, v181 offset:512
	ds_read_b32 v171, v181 offset:768
	ds_read_b32 v172, v181 offset:1024
	ds_read_b32 v173, v181 offset:1280
	ds_read_b32 v174, v181 offset:1536
	ds_read_b32 v175, v181 offset:1792
	s_waitcnt lgkmcnt(0)
	v_lshl_add_u64 v[176:177], v[60:61], 0, v[160:161]
	global_atomic_add_f32 v[176:177], v168, off offset:512
	v_lshl_add_u64 v[178:179], v[60:61], 0, v[162:163]
	global_atomic_add_f32 v[178:179], v169, off offset:512
	v_lshl_add_u64 v[176:177], v[60:61], 0, v[164:165]
	global_atomic_add_f32 v[176:177], v170, off offset:512
	v_lshl_add_u64 v[178:179], v[60:61], 0, v[166:167]
	global_atomic_add_f32 v[178:179], v171, off offset:512
	v_lshl_add_u64 v[176:177], v[60:61], 0, v[160:161]
	global_atomic_add_f32 v[176:177], v172, off offset:576
	v_lshl_add_u64 v[178:179], v[60:61], 0, v[162:163]
	global_atomic_add_f32 v[178:179], v173, off offset:576
	v_lshl_add_u64 v[176:177], v[60:61], 0, v[164:165]
	global_atomic_add_f32 v[176:177], v174, off offset:576
	v_lshl_add_u64 v[178:179], v[60:61], 0, v[166:167]
	global_atomic_add_f32 v[178:179], v175, off offset:576
	ds_write_b128 v180, v[14:17] offset:0
	ds_write_b128 v180, v[10:13] offset:1024
	s_nop 1
	s_waitcnt lgkmcnt(0)
	ds_read_b32 v168, v181 offset:0
	ds_read_b32 v169, v181 offset:256
	ds_read_b32 v170, v181 offset:512
	ds_read_b32 v171, v181 offset:768
	ds_read_b32 v172, v181 offset:1024
	ds_read_b32 v173, v181 offset:1280
	ds_read_b32 v174, v181 offset:1536
	ds_read_b32 v175, v181 offset:1792
	s_waitcnt lgkmcnt(0)
	v_lshl_add_u64 v[176:177], v[50:51], 0, v[160:161]
	global_atomic_add_f32 v[176:177], v168, off offset:512
	v_lshl_add_u64 v[178:179], v[50:51], 0, v[162:163]
	global_atomic_add_f32 v[178:179], v169, off offset:512
	v_lshl_add_u64 v[176:177], v[50:51], 0, v[164:165]
	global_atomic_add_f32 v[176:177], v170, off offset:512
	v_lshl_add_u64 v[178:179], v[50:51], 0, v[166:167]
	global_atomic_add_f32 v[178:179], v171, off offset:512
	v_lshl_add_u64 v[176:177], v[50:51], 0, v[160:161]
	global_atomic_add_f32 v[176:177], v172, off offset:576
	v_lshl_add_u64 v[178:179], v[50:51], 0, v[162:163]
	global_atomic_add_f32 v[178:179], v173, off offset:576
	v_lshl_add_u64 v[176:177], v[50:51], 0, v[164:165]
	global_atomic_add_f32 v[176:177], v174, off offset:576
	v_lshl_add_u64 v[178:179], v[50:51], 0, v[166:167]
	global_atomic_add_f32 v[178:179], v175, off offset:576
	ds_write_b128 v180, v[6:9] offset:0
	ds_write_b128 v180, v[2:5] offset:1024
	s_nop 1
	s_waitcnt lgkmcnt(0)
	ds_read_b32 v168, v181 offset:0
	ds_read_b32 v169, v181 offset:256
	ds_read_b32 v170, v181 offset:512
	ds_read_b32 v171, v181 offset:768
	ds_read_b32 v172, v181 offset:1024
	ds_read_b32 v173, v181 offset:1280
	ds_read_b32 v174, v181 offset:1536
	ds_read_b32 v175, v181 offset:1792
	s_waitcnt lgkmcnt(0)
	v_lshl_add_u64 v[176:177], v[42:43], 0, v[160:161]
	global_atomic_add_f32 v[176:177], v168, off offset:512
	v_lshl_add_u64 v[178:179], v[42:43], 0, v[162:163]
	global_atomic_add_f32 v[178:179], v169, off offset:512
	v_lshl_add_u64 v[176:177], v[42:43], 0, v[164:165]
	global_atomic_add_f32 v[176:177], v170, off offset:512
	v_lshl_add_u64 v[178:179], v[42:43], 0, v[166:167]
	global_atomic_add_f32 v[178:179], v171, off offset:512
	v_lshl_add_u64 v[176:177], v[42:43], 0, v[160:161]
	global_atomic_add_f32 v[176:177], v172, off offset:576
	v_lshl_add_u64 v[178:179], v[42:43], 0, v[162:163]
	global_atomic_add_f32 v[178:179], v173, off offset:576
	v_lshl_add_u64 v[176:177], v[42:43], 0, v[164:165]
	global_atomic_add_f32 v[176:177], v174, off offset:576
	v_lshl_add_u64 v[178:179], v[42:43], 0, v[166:167]
	global_atomic_add_f32 v[178:179], v175, off offset:576
